# fast attention loop: K/V LDS-DMA use scalar base + 32-bit lane offset; five 64-bit VALU adds per iteration become SALU adds, per-lane pointers rebuilt at loop exit
# baseline (speedup 1.0000x reference)
.Lattn_saddr_entry:
	v_readfirstlane_b32 s68, v180
	v_readfirstlane_b32 s69, v181
	v_readfirstlane_b32 s70, v182
	v_readfirstlane_b32 s71, v183
	s_nop 1
	v_subrev_u32_e32 v244, s68, v180
	v_subrev_u32_e32 v245, s70, v182
.Lattn_fast_top:
	v_add_u32_e32 v185, s20, v224
	ds_read_b64_tr_b16 v[176:177], v185 offset:24576
	ds_read_b64_tr_b16 v[178:179], v185 offset:25088
	v_mfma_f32_32x32x16_bf16 v[96:111], v[80:83], v[156:159], v[32:47]
	v_add_f32_e32 v84, v64, v65
	v_add_f32_e32 v84, v66, v84
	v_add_f32_e32 v84, v67, v84
	v_add_f32_e32 v84, v68, v84
	v_add_f32_e32 v84, v69, v84
	v_cvt_pk_bf16_f32 v148, v64, v65
	v_cvt_pk_bf16_f32 v149, v66, v67
	ds_read_b64_tr_b16 v[172:173], v185 offset:28672
	ds_read_b64_tr_b16 v[174:175], v185 offset:29184
	v_add_f32_e32 v64, v70, v84
	v_mfma_f32_32x32x16_bf16 v[80:95], v[164:167], v[156:159], v[32:47]
	v_add_f32_e32 v64, v71, v64
	v_add_f32_e32 v64, v72, v64
	v_add_f32_e32 v128, v73, v64
	v_cvt_pk_bf16_f32 v150, v68, v69
	v_cvt_pk_bf16_f32 v151, v70, v71
	ds_read_b64_tr_b16 v[64:65], v185 offset:25600
	ds_read_b64_tr_b16 v[66:67], v185 offset:26112
	v_mfma_f32_32x32x16_bf16 v[96:111], v[168:171], v[152:155], v[96:111]
	v_add_f32_e32 v68, v74, v128
	v_add_f32_e32 v68, v75, v68
	v_add_f32_e32 v68, v76, v68
	v_add_f32_e32 v128, v77, v68
	v_cvt_pk_bf16_f32 v144, v72, v73
	v_cvt_pk_bf16_f32 v145, v74, v75
	ds_read_b64_tr_b16 v[68:69], v185 offset:29696
	ds_read_b64_tr_b16 v[70:71], v185 offset:30208
	v_mfma_f32_32x32x16_bf16 v[80:95], v[160:163], v[152:155], v[80:95]
	v_add_f32_e32 v72, v78, v128
	v_add_f32_e32 v72, v79, v72
	v_add_f32_e32 v72, v48, v72
	v_add_f32_e32 v128, v49, v72
	v_cvt_pk_bf16_f32 v146, v76, v77
	v_cvt_pk_bf16_f32 v147, v78, v79
	ds_read_b64_tr_b16 v[72:73], v185 offset:26624
	ds_read_b64_tr_b16 v[74:75], v185 offset:27136
	v_mfma_f32_32x32x16_bf16 v[96:111], v[124:127], v[140:143], v[96:111]
	v_add_f32_e32 v76, v50, v128
	v_add_f32_e32 v76, v51, v76
	v_add_f32_e32 v76, v52, v76
	v_add_f32_e32 v76, v53, v76
	v_cvt_pk_bf16_f32 v136, v48, v49
	v_cvt_pk_bf16_f32 v137, v50, v51
	ds_read_b64_tr_b16 v[48:49], v185 offset:30720
	ds_read_b64_tr_b16 v[50:51], v185 offset:31232
	v_mfma_f32_32x32x16_bf16 v[80:95], v[120:123], v[140:143], v[80:95]
	v_add_f32_e32 v76, v54, v76
	v_add_f32_e32 v76, v55, v76
	v_add_f32_e32 v76, v56, v76
	v_add_f32_e32 v76, v57, v76
	v_cvt_pk_bf16_f32 v138, v52, v53
	v_cvt_pk_bf16_f32 v139, v54, v55
	ds_read_b64_tr_b16 v[52:53], v185 offset:27648
	ds_read_b64_tr_b16 v[54:55], v185 offset:28160
	v_mfma_f32_32x32x16_bf16 v[96:111], v[116:119], v[132:135], v[96:111]
	v_add_f32_e32 v76, v58, v76
	v_add_f32_e32 v76, v59, v76
	v_add_f32_e32 v76, v60, v76
	v_add_f32_e32 v76, v61, v76
	v_cvt_pk_bf16_f32 v128, v56, v57
	v_cvt_pk_bf16_f32 v129, v58, v59
	ds_read_b64_tr_b16 v[56:57], v185 offset:31744
	ds_read_b64_tr_b16 v[58:59], v185 offset:32256
	v_mfma_f32_32x32x16_bf16 v[80:95], v[112:115], v[132:135], v[80:95]
	v_add_f32_e32 v76, v62, v76
	v_add_f32_e32 v76, v63, v76
	v_cvt_pk_bf16_f32 v130, v60, v61
	v_cvt_pk_bf16_f32 v131, v62, v63
	s_add_u32 s72, s68, 0x6000
	s_addc_u32 s73, s69, 0
	s_add_i32 m0, s43, s39
	s_nop 0
	global_load_lds_dwordx4 v244, s[72:73]
	s_add_u32 s74, s70, s48
	s_addc_u32 s75, s71, s49
	s_add_i32 m0, s42, s35
	s_nop 0
	global_load_lds_dwordx4 v245, s[74:75]
	v_add_f32_e32 v184, v184, v76
	s_waitcnt lgkmcnt(14)
	v_mfma_f32_32x32x16_bf16 v[0:15], v[148:151], v[176:179], v[0:15]
	v_exp_f32_e32 v96, v96
	v_exp_f32_e32 v97, v97
	v_exp_f32_e32 v98, v98
	v_exp_f32_e32 v99, v99
	s_waitcnt lgkmcnt(12)
	v_mfma_f32_32x32x16_bf16 v[16:31], v[148:151], v[172:175], v[16:31]
	v_exp_f32_e32 v100, v100
	v_exp_f32_e32 v101, v101
	v_exp_f32_e32 v102, v102
	v_exp_f32_e32 v103, v103
	v_add_u32_e32 v76, s42, v225
	ds_read_b128 v[60:63], v76
	ds_read_b128 v[172:175], v76 offset:512
	s_waitcnt lgkmcnt(12)
	v_mfma_f32_32x32x16_bf16 v[0:15], v[144:147], v[64:67], v[0:15]
	v_exp_f32_e32 v104, v104
	v_exp_f32_e32 v105, v105
	v_exp_f32_e32 v106, v106
	v_exp_f32_e32 v107, v107
	ds_read_b128 v[176:179], v76 offset:2048
	ds_read_b128 v[168:171], v76 offset:2560
	s_waitcnt lgkmcnt(12)
	v_mfma_f32_32x32x16_bf16 v[16:31], v[144:147], v[68:71], v[16:31]
	v_exp_f32_e32 v108, v108
	v_exp_f32_e32 v109, v109
	v_exp_f32_e32 v110, v110
	v_exp_f32_e32 v111, v111
	ds_read_b128 v[164:167], v76 offset:4096
	ds_read_b128 v[160:163], v76 offset:4608
	s_waitcnt lgkmcnt(12)
	v_mfma_f32_32x32x16_bf16 v[0:15], v[136:139], v[72:75], v[0:15]
	v_exp_f32_e32 v80, v80
	v_exp_f32_e32 v81, v81
	v_exp_f32_e32 v82, v82
	v_exp_f32_e32 v83, v83
	ds_read_b128 v[124:127], v76 offset:6144
	ds_read_b128 v[120:123], v76 offset:6656
	s_waitcnt lgkmcnt(12)
	v_mfma_f32_32x32x16_bf16 v[16:31], v[136:139], v[48:51], v[16:31]
	v_exp_f32_e32 v84, v84
	v_exp_f32_e32 v85, v85
	v_exp_f32_e32 v86, v86
	v_exp_f32_e32 v87, v87
	s_waitcnt lgkmcnt(10)
	v_mfma_f32_32x32x16_bf16 v[0:15], v[128:131], v[52:55], v[0:15]
	v_exp_f32_e32 v88, v88
	v_exp_f32_e32 v89, v89
	v_exp_f32_e32 v90, v90
	v_exp_f32_e32 v91, v91
	s_waitcnt lgkmcnt(8)
	v_mfma_f32_32x32x16_bf16 v[16:31], v[128:131], v[56:59], v[16:31]
	v_exp_f32_e32 v92, v92
	v_exp_f32_e32 v93, v93
	v_exp_f32_e32 v94, v94
	v_exp_f32_e32 v95, v95
	s_waitcnt vmcnt(2) lgkmcnt(0)
	s_barrier
	s_add_i32 s20, s42, 0x2000
	s_cmpk_lg_i32 s42, 0x4000
	s_cselect_b32 s44, s20, 0
	v_add_u32_e32 v185, s43, v224
	ds_read_b64_tr_b16 v[116:117], v185 offset:24576
	ds_read_b64_tr_b16 v[118:119], v185 offset:25088
	v_mfma_f32_32x32x16_bf16 v[64:79], v[60:63], v[156:159], v[32:47]
	v_add_f32_e32 v48, v96, v97
	v_add_f32_e32 v48, v98, v48
	v_add_f32_e32 v48, v99, v48
	v_add_f32_e32 v48, v100, v48
	v_add_f32_e32 v48, v101, v48
	v_cvt_pk_bf16_f32 v148, v96, v97
	v_cvt_pk_bf16_f32 v149, v98, v99
	ds_read_b64_tr_b16 v[112:113], v185 offset:28672
	ds_read_b64_tr_b16 v[114:115], v185 offset:29184
	v_add_f32_e32 v48, v102, v48
	v_add_f32_e32 v48, v103, v48
	v_add_f32_e32 v48, v104, v48
	v_add_f32_e32 v128, v105, v48
	v_mfma_f32_32x32x16_bf16 v[48:63], v[172:175], v[156:159], v[32:47]
	v_cvt_pk_bf16_f32 v150, v100, v101
	v_cvt_pk_bf16_f32 v151, v102, v103
	ds_read_b64_tr_b16 v[96:97], v185 offset:25600
	ds_read_b64_tr_b16 v[98:99], v185 offset:26112
	v_mfma_f32_32x32x16_bf16 v[64:79], v[176:179], v[152:155], v[64:79]
	v_add_f32_e32 v100, v106, v128
	v_add_f32_e32 v100, v107, v100
	v_add_f32_e32 v100, v108, v100
	v_add_f32_e32 v128, v109, v100
	v_cvt_pk_bf16_f32 v144, v104, v105
	v_cvt_pk_bf16_f32 v145, v106, v107
	ds_read_b64_tr_b16 v[100:101], v185 offset:29696
	ds_read_b64_tr_b16 v[102:103], v185 offset:30208
	v_mfma_f32_32x32x16_bf16 v[48:63], v[168:171], v[152:155], v[48:63]
	v_add_f32_e32 v104, v110, v128
	v_add_f32_e32 v104, v111, v104
	v_add_f32_e32 v104, v80, v104
	v_add_f32_e32 v128, v81, v104
	v_cvt_pk_bf16_f32 v146, v108, v109
	v_cvt_pk_bf16_f32 v147, v110, v111
	ds_read_b64_tr_b16 v[104:105], v185 offset:26624
	ds_read_b64_tr_b16 v[106:107], v185 offset:27136
	v_mfma_f32_32x32x16_bf16 v[64:79], v[164:167], v[140:143], v[64:79]
	v_add_f32_e32 v108, v82, v128
	v_add_f32_e32 v108, v83, v108
	v_add_f32_e32 v108, v84, v108
	v_add_f32_e32 v128, v85, v108
	v_cvt_pk_bf16_f32 v136, v80, v81
	v_cvt_pk_bf16_f32 v137, v82, v83
	ds_read_b64_tr_b16 v[108:109], v185 offset:30720
	ds_read_b64_tr_b16 v[110:111], v185 offset:31232
	v_mfma_f32_32x32x16_bf16 v[48:63], v[160:163], v[140:143], v[48:63]
	v_add_f32_e32 v80, v86, v128
	v_add_f32_e32 v80, v87, v80
	v_add_f32_e32 v80, v88, v80
	v_add_f32_e32 v80, v89, v80
	v_cvt_pk_bf16_f32 v138, v84, v85
	v_cvt_pk_bf16_f32 v139, v86, v87
	ds_read_b64_tr_b16 v[84:85], v185 offset:27648
	ds_read_b64_tr_b16 v[86:87], v185 offset:28160
	v_mfma_f32_32x32x16_bf16 v[64:79], v[124:127], v[132:135], v[64:79]
	v_add_f32_e32 v80, v90, v80
	v_add_f32_e32 v80, v91, v80
	v_add_f32_e32 v80, v92, v80
	v_add_f32_e32 v80, v93, v80
	v_cvt_pk_bf16_f32 v128, v88, v89
	v_cvt_pk_bf16_f32 v129, v90, v91
	ds_read_b64_tr_b16 v[88:89], v185 offset:31744
	ds_read_b64_tr_b16 v[90:91], v185 offset:32256
	v_mfma_f32_32x32x16_bf16 v[48:63], v[120:123], v[132:135], v[48:63]
	v_add_f32_e32 v80, v94, v80
	v_add_f32_e32 v80, v95, v80
	v_add_f32_e32 v82, 0, v80
	v_cvt_pk_bf16_f32 v130, v92, v93
	v_cvt_pk_bf16_f32 v131, v94, v95
	s_add_u32 s72, s68, s88
	s_addc_u32 s73, s69, s89
	s_add_i32 m0, s42, s39
	s_nop 0
	global_load_lds_dwordx4 v244, s[72:73]
	s_add_u32 s70, s70, 0x4000
	s_addc_u32 s71, s71, 0
	s_add_i32 m0, s44, s35
	s_nop 0
	global_load_lds_dwordx4 v245, s[70:71]
	v_add_f32_e32 v184, v184, v82
	s_waitcnt lgkmcnt(14)
	v_mfma_f32_32x32x16_bf16 v[0:15], v[148:151], v[116:119], v[0:15]
	v_exp_f32_e32 v64, v64
	v_exp_f32_e32 v65, v65
	v_exp_f32_e32 v66, v66
	v_exp_f32_e32 v67, v67
	s_waitcnt lgkmcnt(12)
	v_mfma_f32_32x32x16_bf16 v[16:31], v[148:151], v[112:115], v[16:31]
	v_exp_f32_e32 v68, v68
	v_exp_f32_e32 v69, v69
	v_exp_f32_e32 v70, v70
	v_exp_f32_e32 v71, v71
	v_add_u32_e32 v92, s44, v225
	ds_read_b128 v[80:83], v92
	ds_read_b128 v[164:167], v92 offset:512
	s_waitcnt lgkmcnt(12)
	v_mfma_f32_32x32x16_bf16 v[0:15], v[144:147], v[96:99], v[0:15]
	v_exp_f32_e32 v72, v72
	v_exp_f32_e32 v73, v73
	v_exp_f32_e32 v74, v74
	v_exp_f32_e32 v75, v75
	ds_read_b128 v[168:171], v92 offset:2048
	ds_read_b128 v[160:163], v92 offset:2560
	s_waitcnt lgkmcnt(12)
	v_mfma_f32_32x32x16_bf16 v[16:31], v[144:147], v[100:103], v[16:31]
	v_exp_f32_e32 v76, v76
	v_exp_f32_e32 v77, v77
	v_exp_f32_e32 v78, v78
	v_exp_f32_e32 v79, v79
	ds_read_b128 v[124:127], v92 offset:4096
	ds_read_b128 v[120:123], v92 offset:4608
	s_waitcnt lgkmcnt(12)
	v_mfma_f32_32x32x16_bf16 v[0:15], v[136:139], v[104:107], v[0:15]
	v_exp_f32_e32 v48, v48
	v_exp_f32_e32 v49, v49
	v_exp_f32_e32 v50, v50
	v_exp_f32_e32 v51, v51
	ds_read_b128 v[116:119], v92 offset:6144
	ds_read_b128 v[112:115], v92 offset:6656
	s_waitcnt lgkmcnt(12)
	v_mfma_f32_32x32x16_bf16 v[16:31], v[136:139], v[108:111], v[16:31]
	v_exp_f32_e32 v52, v52
	v_exp_f32_e32 v53, v53
	v_exp_f32_e32 v54, v54
	v_exp_f32_e32 v55, v55
	s_waitcnt lgkmcnt(10)
	v_mfma_f32_32x32x16_bf16 v[0:15], v[128:131], v[84:87], v[0:15]
	v_exp_f32_e32 v56, v56
	v_exp_f32_e32 v57, v57
	v_exp_f32_e32 v58, v58
	v_exp_f32_e32 v59, v59
	s_waitcnt lgkmcnt(8)
	v_mfma_f32_32x32x16_bf16 v[16:31], v[128:131], v[88:91], v[16:31]
	v_exp_f32_e32 v60, v60
	v_exp_f32_e32 v61, v61
	v_exp_f32_e32 v62, v62
	v_exp_f32_e32 v63, v63
	s_waitcnt vmcnt(2) lgkmcnt(0)
	s_barrier
	s_add_i32 s20, s44, 0x2000
	s_cmpk_lg_i32 s44, 0x4000
	s_cselect_b32 s21, s20, 0
	s_add_i32 s41, s41, 2
	s_mov_b64 s[30:31], 0x4000
	s_add_u32 s68, s68, 0x4000
	s_addc_u32 s69, s69, 0
	s_cmp_lt_u32 s41, 57
	s_cbranch_scc0 .Lattn_saddr_exit
	s_mov_b32 s20, s42
	s_mov_b32 s43, s44
	s_mov_b32 s42, s21
	s_branch .Lattn_fast_top
.Lattn_saddr_exit:
	v_mov_b32_e32 v246, v244
	v_mov_b32_e32 v247, 0
	v_lshl_add_u64 v[180:181], s[68:69], 0, v[246:247]
	v_mov_b32_e32 v246, v245
	v_lshl_add_u64 v[182:183], s[70:71], 0, v[246:247]
	s_branch .LBB0_401
